# v14: v13 plus one static s_setprio 1 at entry for workgroups with blockIdx >= 256 (one of the two co-resident waves per SIMD prioritized)
# baseline (speedup 1.0000x reference)
; #define LDSP(T, p) ((__attribute__((address_space(3))) T*)(p))
; #define LAS __attribute__((address_space(3)))
; DI unsigned xb_add(unsigned* p, unsigned v) { return __hip_atomic_fetch_add(p, v, __ATOMIC_RELAXED, __HIP_MEMORY_SCOPE_AGENT); }
; DI unsigned xb_xcc_id() { return (unsigned)__builtin_amdgcn_s_getreg((3 << 11) | 20) & 0xFu; }
; DI XcdBarrier xcd_barrier_post(unsigned* bar, volatile LAS unsigned* st) {
;   XcdBarrier b; b.bar = bar; b.x = xb_xcc_id(); b.st = st;
;   if (threadIdx.x == 0) (void)xb_add(&bar[XB_XCNT(b.x)], 1u);
;   return b;
; }
; __global__ void __launch_bounds__(256, 2) mega(Params p) {
;   cg::grid_group grid = cg::this_grid();
;   __shared__ __attribute__((aligned(16))) char smem[65536 + 16];
;   char* ws = p.ws;
;   if (threadIdx.x == 0) { *(unsigned*)(smem + 65536) = 0u; *(unsigned*)(smem + 65540) = 0u; }
;   __syncthreads();
;   const XcdBarrier xb = xcd_barrier_post((unsigned*)(ws + A_BAR), (volatile LAS unsigned*)LDSP(unsigned, smem + 65536));
_Z4mega6Params:
	s_load_dwordx8 s[48:55], s[0:1], 0xc0
	s_load_dwordx4 s[88:91], s[0:1], 0xe0
	s_load_dwordx2 s[56:57], s[0:1], 0xf0
	s_mov_b32 s82, s2
	s_add_u32 s2, s0, 0xf0
	v_and_b32_e32 v190, 0x3ff, v0
	s_addc_u32 s3, s1, 0
	s_cmpk_lt_u32 s82, 0x100
	s_cbranch_scc1 .Lprio_skip
	s_setprio 1
.Lprio_skip:
	v_cmp_ne_u32_e64 s[6:7], 0, v190
	v_cmp_eq_u32_e64 s[8:9], 0, v190
	s_mov_b64 s[4:5], exec
	s_nop 0
	v_writelane_b32 v250, s8, 0
	s_nop 1
	v_writelane_b32 v250, s9, 1
	s_and_b64 s[8:9], s[4:5], s[8:9]
	s_mov_b64 exec, s[8:9]
	v_mov_b32_e32 v2, 0
	v_mov_b32_e32 v3, v2
	v_mov_b32_e32 v1, 0x10000
	ds_write_b64 v1, v[2:3]
	s_or_b64 exec, exec, s[4:5]
	s_load_dword s46, s[0:1], 0xf8
	s_waitcnt lgkmcnt(0)
	s_barrier
	s_add_u32 s4, s90, 0x33a40000
	s_getreg_b32 s8, hwreg(HW_REG_XCC_ID, 0, 4)
	s_addc_u32 s5, s91, 0
	s_and_b32 s33, s8, 15
	s_mov_b64 s[8:9], exec
	v_readlane_b32 s10, v250, 0
	v_readlane_b32 s11, v250, 1
	s_and_b64 s[10:11], s[8:9], s[10:11]
	s_mov_b64 exec, s[10:11]
	s_cbranch_execz .LBB0_5
	s_mov_b64 s[10:11], exec
	v_mbcnt_lo_u32_b32 v1, s10, 0
	v_mbcnt_hi_u32_b32 v1, s11, v1
	v_cmp_eq_u32_e32 vcc, 0, v1
	s_and_b64 s[12:13], exec, vcc
	s_mov_b64 exec, s[12:13]
	s_cbranch_execz .LBB0_5
	s_lshl_b32 s12, s33, 8
	s_bcnt1_i32_b64 s10, s[10:11]
	v_mov_b32_e32 v1, s12
	v_mov_b32_e32 v2, s10
	global_atomic_add v1, v2, s[4:5] offset:1024
